# GDN recurrence loop: counted vmcnt waits (prefetch of the fourth operand set stays in flight) instead of the vmcnt(0) drain at the loop head, added to the rebalanced version
# speedup vs baseline: 1.0346x; 1.0046x over previous
; #define LAS __attribute__((address_space(3)))
; DI void gdn_b_prompt(const Ctx& C, int ch0, int row0, int h, int slice, float* sout) {
;     const int lane = C.lane, w = C.wave, n = lane & 15, quad = lane >> 4, mt = w & 3;
;     LAS bf16_t* ST = (LAS bf16_t*)(C.lds + GB_ST); LAS bf16_t* VT_ = (LAS bf16_t*)(C.lds + GB_VT);
;     const bf16_t* p4 = (w < 4 ? WSP(bf16_t, WS_GW) : WSP(bf16_t, WS_GQD)) + (size_t)ch0 * 8192 + mt * 2048 + lane * 8;
;     const bf16_t* p2 = WSP(bf16_t, WS_GATT) + (size_t)ch0 * 4096 + (w < 4 ? 0 : mt * 1024 + lane * 8);
;     const bf16_t* pK = WSP(bf16_t, WS_GKDT) + (size_t)ch0 * 8192 + w * 1024 + lane * 8;
;     const bf16_t* pU = WSP(bf16_t, WS_GU) + (size_t)ch0 * 8192 + (w < 4 ? (slice * 16 + n) * 64 + 16 * mt + 4 * quad : 0);
;     const float* pG = WSP(float, WS_GTOT) + ch0;
;     bf16_t* pO = WSP(bf16_t, WS_ACT) + (size_t)(row0 + 16 * mt + 4 * quad) * DM + 1024 + h * 128 + 16 * slice + n;
;     f32x4 sacc = {0.f, 0.f, 0.f, 0.f};
;     ...
;     GbSet s0, s1, s2, s3;
;     GBL(s0, 0); GBL(s1, 1); GBL(s2, 2); GBL(s3, 3);
.LBB0_654:
	s_lshl_b32 s4, s59, 11
	s_and_b32 s39, s4, 0x7000
	s_lshl_b32 s4, s65, 1
	s_and_b32 s4, s4, 14
	s_ashr_i32 s44, s65, 6
	s_add_i32 s38, s4, s44
	s_lshl_b32 s4, s38, 8
	s_ashr_i32 s5, s4, 31
	s_lshl_b64 s[42:43], s[4:5], 14
	s_lshr_b32 s0, s59, 1
	s_bfe_u32 s66, s65, 0x30003
	v_lshl_add_u64 v[168:169], v[150:151], 0, s[42:43]
	s_lshl_b32 s0, s0, 8
	s_lshl_b64 s[40:41], s[4:5], 13
	v_lshl_or_b32 v0, s66, 10, v189
	v_add_co_u32_e32 v4, vcc, s61, v168
	v_lshl_add_u64 v[170:171], v[152:153], 0, s[40:41]
	v_lshl_add_u64 v[172:173], v[154:155], 0, s[42:43]
	s_add_u32 s42, s49, s42
	v_cndmask_b32_e64 v0, 0, v0, s[2:3]
	v_addc_co_u32_e32 v5, vcc, 0, v169, vcc
	s_addc_u32 s43, s56, s43
	global_load_dwordx4 v[36:39], v[168:169], off
	global_load_dwordx4 v[40:43], v[168:169], off offset:1024
	global_load_dwordx4 v[32:35], v[168:169], off offset:2048
	global_load_dwordx4 v[28:31], v[168:169], off offset:3072
	s_waitcnt vmcnt(0)
	v_lshlrev_b32_e32 v146, 1, v0
	global_load_dwordx4 v[12:15], v[170:171], off
	global_load_dwordx4 v[8:11], v[170:171], off offset:1024
	global_load_dwordx4 v[0:3], v[172:173], off
	global_load_dwordx4 v[128:131], v[172:173], off offset:1024
	global_load_dwordx2 v[178:179], v146, s[42:43]
	global_load_dwordx4 v[60:63], v[4:5], off
	global_load_dwordx4 v[64:67], v[4:5], off offset:1024
	global_load_dwordx4 v[56:59], v[4:5], off offset:2048
	global_load_dwordx4 v[52:55], v[4:5], off offset:3072
	v_add_co_u32_e32 v4, vcc, s62, v170
	v_lshl_add_u64 v[174:175], s[42:43], 0, v[146:147]
	s_nop 0
	v_addc_co_u32_e32 v5, vcc, 0, v171, vcc
	v_add_co_u32_e32 v16, vcc, s61, v172
	global_load_dwordx4 v[24:27], v[4:5], off
	global_load_dwordx4 v[20:23], v[4:5], off offset:1024
	v_addc_co_u32_e32 v17, vcc, 0, v173, vcc
	global_load_dwordx4 v[4:7], v[16:17], off
	global_load_dwordx4 v[96:99], v[16:17], off offset:1024
	v_add_co_u32_e32 v16, vcc, s61, v174
	s_lshl_b64 s[4:5], s[4:5], 2
	s_nop 0
	v_addc_co_u32_e32 v17, vcc, 0, v175, vcc
	s_add_u32 s40, s57, s4
	v_add_co_u32_e32 v18, vcc, s63, v168
	s_addc_u32 s41, s58, s5
	s_nop 0
	v_addc_co_u32_e32 v19, vcc, 0, v169, vcc
	global_load_dwordx3 v[144:146], v147, s[40:41]
	global_load_dwordx2 v[180:181], v[16:17], off
	global_load_dwordx4 v[72:75], v[18:19], off
	global_load_dwordx4 v[80:83], v[18:19], off offset:1024
	global_load_dwordx4 v[68:71], v[18:19], off offset:2048
	v_add_co_u32_e32 v16, vcc, s61, v170
	s_add_u32 s4, s40, 12
	s_nop 0
	v_addc_co_u32_e32 v17, vcc, 0, v171, vcc
	v_add_co_u32_e32 v84, vcc, s63, v172
	global_load_dwordx4 v[76:79], v[18:19], off offset:3072
	global_load_dwordx4 v[44:47], v[16:17], off
	v_addc_co_u32_e32 v85, vcc, 0, v173, vcc
	v_add_co_u32_e32 v88, vcc, s63, v174
	global_load_dwordx4 v[48:51], v[16:17], off offset:1024
	s_nop 0
	global_load_dwordx4 v[16:19], v[84:85], off
	v_addc_co_u32_e32 v89, vcc, 0, v175, vcc
	global_load_dwordx4 v[84:87], v[84:85], off offset:1024
	s_nop 0
	global_load_dwordx2 v[182:183], v[88:89], off
	v_add_co_u32_e32 v88, vcc, s64, v174
	s_addc_u32 s5, s41, 0
	s_nop 0
	v_addc_co_u32_e32 v89, vcc, 0, v175, vcc
	global_load_dwordx2 v[184:185], v[88:89], off
	s_lshl_b32 s42, s44, 11
	s_add_i32 s39, s39, s42
	s_and_b32 s39, s39, 0xffffc000
	v_add_u32_e32 v88, s39, v196
	s_lshl_b32 s39, s44, 7
	s_add_i32 s0, s0, s39
	v_ashrrev_i32_e32 v89, 31, v88
	s_lshl_b32 s0, s0, 1
	v_lshlrev_b64 v[88:89], 12, v[88:89]
	s_and_b32 s0, s0, 0x700
	v_or_b32_e32 v88, s0, v88
	v_lshl_or_b32 v88, s66, 5, v88
	v_lshl_add_u64 v[100:101], v[168:169], 0, s[10:11]
	v_lshl_add_u64 v[102:103], v[168:169], 0, s[12:13]
	v_lshl_add_u64 v[104:105], v[168:169], 0, s[14:15]
	v_lshl_add_u64 v[106:107], v[168:169], 0, s[16:17]
	v_lshl_add_u64 v[92:93], v[170:171], 0, s[18:19]
	v_lshl_add_u64 v[94:95], v[170:171], 0, s[20:21]
	v_lshl_add_u64 v[190:191], v[172:173], 0, s[10:11]
	v_lshl_add_u64 v[192:193], v[172:173], 0, s[12:13]
	v_lshl_add_u64 v[176:177], v[164:165], 0, v[88:89]
	s_mov_b32 s39, s1
	v_mov_b32_e32 v136, 0
	v_mov_b32_e32 v137, v147
	v_mov_b32_e32 v138, v147
	v_mov_b32_e32 v139, v147
	s_waitcnt vmcnt(0)
	s_branch .LBB0_656

.LBB0_656:
	global_load_dword v186, v147, s[4:5]
	global_load_dwordx4 v[120:123], v[100:101], off
	global_load_dwordx4 v[124:127], v[102:103], off
	global_load_dwordx4 v[116:119], v[104:105], off
	global_load_dwordx4 v[112:115], v[106:107], off
	s_nop 0
	global_load_dwordx4 v[104:107], v[92:93], off
	global_load_dwordx4 v[100:103], v[94:95], off
	s_nop 0
	global_load_dwordx4 v[92:95], v[190:191], off
	global_load_dwordx4 v[88:91], v[192:193], off
	v_cvt_pk_bf16_f32 v108, v136, v137
	v_cvt_pk_bf16_f32 v109, v138, v139
	ds_write_b64 v194, v[108:109]
	s_waitcnt lgkmcnt(0)
	s_barrier
	ds_read_b128 v[108:111], v197
	ds_read_b128 v[132:135], v197 offset:64
	s_andn2_b64 vcc, exec, s[2:3]
	s_waitcnt lgkmcnt(0)
	v_mfma_f32_16x16x32_bf16 v[36:39], v[36:39], v[108:111], 0
	v_mfma_f32_16x16x32_bf16 v[36:39], v[40:43], v[132:135], v[36:39]
	ds_read_b128 v[40:43], v197 offset:128
	ds_read_b128 v[108:111], v197 offset:192
	s_waitcnt lgkmcnt(1)
	v_mfma_f32_16x16x32_bf16 v[32:35], v[32:35], v[40:43], v[36:39]
	s_nop 3
	v_cndmask_b32_e64 v36, 0, 1, s[2:3]
	s_waitcnt lgkmcnt(0)
	v_mfma_f32_16x16x32_bf16 v[28:31], v[28:31], v[108:111], v[32:35]
	v_cmp_ne_u32_e64 s[4:5], 1, v36
	s_cbranch_vccnz .LBB0_658
	s_nop 0
	v_and_b32_e32 v33, 0xffff0000, v178
	v_lshlrev_b32_e32 v32, 16, v178
	v_and_b32_e32 v35, 0xffff0000, v179
	v_lshlrev_b32_e32 v34, 16, v179
	s_nop 0
	v_pk_add_f32 v[32:33], v[32:33], v[28:29] neg_lo:[0,1] neg_hi:[0,1]
	v_pk_add_f32 v[34:35], v[34:35], v[30:31] neg_lo:[0,1] neg_hi:[0,1]
	v_cvt_pk_bf16_f32 v32, v32, v33
	v_cvt_pk_bf16_f32 v33, v34, v35
	ds_write_b64 v198, v[32:33] offset:4352

.LBB0_668:
	s_min_u32 s68, s39, 0xfa
	s_add_i32 s44, s68, 5
	s_lshl_b32 s0, s44, 13
	s_lshl_b32 s44, s44, 14
	s_mov_b32 s45, s1
	v_lshl_add_u64 v[20:21], v[168:169], 0, s[44:45]
	global_load_dwordx4 v[60:63], v[20:21], off
	global_load_dwordx4 v[64:67], v[20:21], off offset:1024
	global_load_dwordx4 v[56:59], v[20:21], off offset:2048
	global_load_dwordx4 v[52:55], v[20:21], off offset:3072
	v_pk_mul_f32 v[20:21], v[144:145], v[128:129] op_sel:[1,0]
	v_pk_mul_f32 v[22:23], v[144:145], v[130:131] op_sel:[1,0]
	v_lshl_add_u64 v[140:141], v[174:175], 0, s[44:45]
	s_and_b64 vcc, exec, s[4:5]
	s_waitcnt lgkmcnt(1)
	v_mfma_f32_16x16x32_bf16 v[128:131], v[4:7], v[132:135], v[20:23]
	v_lshl_add_u64 v[4:5], v[170:171], 0, s[0:1]
	v_lshl_add_u64 v[132:133], v[172:173], 0, s[44:45]
	s_lshl_b32 s0, s68, 2
	global_load_dwordx4 v[24:27], v[4:5], off
	global_load_dwordx4 v[20:23], v[4:5], off offset:1024
	s_nop 0
	global_load_dwordx4 v[4:7], v[132:133], off
	s_nop 0
	global_load_dwordx4 v[132:135], v[132:133], off offset:1024
	v_mov_b32_e32 v142, s0
	global_load_dwordx2 v[180:181], v[140:141], off
	global_load_dword v145, v142, s[40:41] offset:20
	s_waitcnt lgkmcnt(0)
	v_mfma_f32_16x16x32_bf16 v[96:99], v[96:99], v[136:139], v[128:131]
	s_nop 7
	v_cvt_pk_bf16_f32 v128, v96, v97
	v_cvt_pk_bf16_f32 v129, v98, v99
	ds_write_b64 v194, v[128:129]
	s_waitcnt lgkmcnt(0)
	s_barrier
	s_waitcnt vmcnt(30)
	ds_read_b128 v[128:131], v187
	ds_read_b128 v[136:139], v187 offset:64
	s_waitcnt lgkmcnt(1)
	v_mfma_f32_16x16x32_bf16 v[72:75], v[72:75], v[128:131], 0
	s_waitcnt lgkmcnt(0)
	v_mfma_f32_16x16x32_bf16 v[72:75], v[80:83], v[136:139], v[72:75]
	ds_read_b128 v[80:83], v187 offset:128
	ds_read_b128 v[128:131], v187 offset:192
	s_waitcnt lgkmcnt(1)
	v_mfma_f32_16x16x32_bf16 v[68:71], v[68:71], v[80:83], v[72:75]
	s_waitcnt lgkmcnt(0)
	v_mfma_f32_16x16x32_bf16 v[68:71], v[76:79], v[128:131], v[68:71]
	s_cbranch_vccnz .LBB0_670
	s_nop 0
	v_and_b32_e32 v73, 0xffff0000, v182
	v_lshlrev_b32_e32 v72, 16, v182
	v_and_b32_e32 v75, 0xffff0000, v183
	v_lshlrev_b32_e32 v74, 16, v183
	s_nop 1
	v_pk_add_f32 v[72:73], v[72:73], v[68:69] neg_lo:[0,1] neg_hi:[0,1]
	v_pk_add_f32 v[74:75], v[74:75], v[70:71] neg_lo:[0,1] neg_hi:[0,1]
	v_cvt_pk_bf16_f32 v72, v72, v73
	v_cvt_pk_bf16_f32 v73, v74, v75
	ds_write_b64 v195, v[72:73] offset:4352

.LBB0_674:
	s_min_u32 s68, s39, 0xf9
	s_add_i32 s44, s68, 6
	s_lshl_b32 s0, s44, 13
	s_lshl_b32 s44, s44, 14
	s_mov_b32 s45, s1
	v_lshl_add_u64 v[44:45], v[168:169], 0, s[44:45]
	global_load_dwordx4 v[72:75], v[44:45], off
	global_load_dwordx4 v[80:83], v[44:45], off offset:1024
	global_load_dwordx4 v[68:71], v[44:45], off offset:2048
	global_load_dwordx4 v[76:79], v[44:45], off offset:3072
	v_pk_mul_f32 v[46:47], v[146:147], v[98:99] op_sel_hi:[0,1]
	v_pk_mul_f32 v[44:45], v[146:147], v[96:97] op_sel_hi:[0,1]
	s_and_b64 vcc, exec, s[4:5]
	s_waitcnt lgkmcnt(1)
	v_mfma_f32_16x16x32_bf16 v[96:99], v[16:19], v[136:139], v[44:47]
	v_lshl_add_u64 v[16:17], v[170:171], 0, s[0:1]
	v_lshl_add_u64 v[136:137], v[172:173], 0, s[44:45]
	s_nop 0
	global_load_dwordx4 v[44:47], v[16:17], off
	global_load_dwordx4 v[48:51], v[16:17], off offset:1024
	s_nop 0
	global_load_dwordx4 v[16:19], v[136:137], off
	global_load_dwordx4 v[140:143], v[136:137], off offset:1024
	v_lshl_add_u64 v[136:137], v[174:175], 0, s[44:45]
	s_lshl_b32 s0, s68, 2
	v_mov_b32_e32 v138, s0
	global_load_dwordx2 v[182:183], v[136:137], off
	global_load_dword v146, v138, s[40:41] offset:24
	s_waitcnt lgkmcnt(0)
	v_mfma_f32_16x16x32_bf16 v[84:87], v[84:87], v[128:131], v[96:99]
	s_nop 7
	v_cvt_pk_bf16_f32 v96, v84, v85
	v_cvt_pk_bf16_f32 v97, v86, v87
	ds_write_b64 v194, v[96:97]
	s_waitcnt lgkmcnt(0)
	s_barrier
	s_waitcnt vmcnt(30)
	ds_read_b128 v[96:99], v187
	ds_read_b128 v[128:131], v187 offset:64
	s_waitcnt lgkmcnt(1)
	v_mfma_f32_16x16x32_bf16 v[96:99], v[120:123], v[96:99], 0
	s_waitcnt lgkmcnt(0)
	v_mfma_f32_16x16x32_bf16 v[96:99], v[124:127], v[128:131], v[96:99]
	ds_read_b128 v[120:123], v187 offset:128
	ds_read_b128 v[124:127], v187 offset:192
	s_waitcnt lgkmcnt(1)
	v_mfma_f32_16x16x32_bf16 v[96:99], v[116:119], v[120:123], v[96:99]
	s_waitcnt lgkmcnt(0)
	v_mfma_f32_16x16x32_bf16 v[116:119], v[112:115], v[124:127], v[96:99]
	s_cbranch_vccnz .LBB0_676
	s_nop 4
	v_and_b32_e32 v97, 0xffff0000, v184
	v_lshlrev_b32_e32 v96, 16, v184
	v_and_b32_e32 v99, 0xffff0000, v185
	v_lshlrev_b32_e32 v98, 16, v185
	v_pk_add_f32 v[96:97], v[96:97], v[116:117] neg_lo:[0,1] neg_hi:[0,1]
	v_pk_add_f32 v[98:99], v[98:99], v[118:119] neg_lo:[0,1] neg_hi:[0,1]
	v_cvt_pk_bf16_f32 v96, v96, v97
	v_cvt_pk_bf16_f32 v97, v98, v99
	ds_write_b64 v195, v[96:97] offset:4352
